# v6 + P8 row pass: router-partial tiles 0..2 staged by coalesced LDS-DMA and read via ds_read_b128 instead of 64B-strided global loads; norm2 fill loads issued together
# speedup vs baseline: 1.0043x; 1.0043x over previous
.LBB0_1394:
	global_load_dword v72, v[68:69], off
	global_load_dword v73, v[66:67], off
	global_load_dword v255, v[66:67], off offset:-4096
	v_add_co_u32_e32 v70, vcc, 0x200, v70
	s_xor_b64 s[10:11], vcc, -1
	s_and_b64 s[10:11], exec, s[10:11]
	v_lshl_add_u64 v[68:69], v[68:69], 0, s[96:97]
	s_or_b64 s[30:31], s[10:11], s[30:31]
	s_waitcnt vmcnt(0)
	v_add_f32_e32 v73, 1.0, v73
	v_mul_f32_e32 v72, v72, v73
	v_mov_b32_e32 v73, v255
	v_lshl_add_u64 v[66:67], v[66:67], 0, s[96:97]
	s_waitcnt vmcnt(0)
	ds_write2st64_b32 v71, v72, v73 offset1:16
	v_add_u32_e32 v71, 0x800, v71
	s_andn2_b64 exec, exec, s[30:31]
	s_cbranch_execnz .LBB0_1394
	s_or_b64 exec, exec, s[30:31]
	s_and_b32 s10, s8, 7
	s_lshl_b32 s3, s10, 6
	v_mov_b32_e32 v78, s3
	global_load_dwordx4 v[66:69], v78, s[94:95]
	global_load_dwordx4 v[70:73], v78, s[94:95] offset:16
	global_load_dwordx4 v[74:77], v78, s[94:95] offset:32
	s_nop 0
	global_load_dwordx4 v[78:81], v78, s[94:95] offset:48
	s_lshr_b32 s11, s8, 4
	s_bfe_u32 s12, s8, 0x40004
	s_cmp_eq_u32 s12, 0
	s_cselect_b64 s[30:31], -1, 0
	s_cmp_eq_u32 s12, 1
	s_cselect_b64 s[34:35], -1, 0
	s_cmp_eq_u32 s12, 2
	s_cselect_b64 s[36:37], -1, 0
	s_cmp_eq_u32 s12, 3
	s_cselect_b64 s[38:39], -1, 0
	s_cmp_eq_u32 s12, 4
	s_cselect_b64 s[40:41], -1, 0
	s_cmp_eq_u32 s12, 5
	s_cselect_b64 s[42:43], -1, 0
	s_cmp_eq_u32 s12, 6
	s_cselect_b64 s[44:45], -1, 0
	s_cmp_eq_u32 s12, 7
	s_cselect_b64 s[46:47], -1, 0
	s_cmp_eq_u32 s12, 8
	s_cselect_b64 s[48:49], -1, 0
	s_cmp_eq_u32 s12, 9
	s_cselect_b64 s[50:51], -1, 0
	s_cmp_eq_u32 s12, 10
	s_cselect_b64 s[52:53], -1, 0
	s_cmp_eq_u32 s12, 11
	s_cselect_b64 s[54:55], -1, 0
	s_cmp_eq_u32 s12, 12
	s_cselect_b64 s[56:57], -1, 0
	s_cmp_eq_u32 s12, 13
	v_lshl_or_b32 v176, s92, 11, v0
	s_cselect_b64 s[58:59], -1, 0
	s_cmp_eq_u32 s12, 14
	v_lshlrev_b32_e32 v134, 2, v176
	s_cselect_b64 s[60:61], -1, 0
	s_cmp_eq_u32 s12, 15
	v_readlane_b32 s68, v252, 42
	v_lshlrev_b32_e32 v156, 6, v176
	v_mov_b32_e32 v157, v135
	s_mov_b64 s[86:87], -1
	s_mov_b64 s[66:67], 0
	s_cselect_b64 s[62:63], -1, 0
	v_mov_b32_e32 v177, v145
	v_mov_b64_e32 v[158:159], v[134:135]
	v_mov_b32_e32 v134, v165
	v_readlane_b32 s82, v252, 56
	v_readlane_b32 s83, v252, 57
	v_readlane_b32 s69, v252, 43
	v_readlane_b32 s70, v252, 44
	v_readlane_b32 s71, v252, 45
	v_readlane_b32 s72, v252, 46
	v_readlane_b32 s73, v252, 47
	v_readlane_b32 s74, v252, 48
	v_readlane_b32 s75, v252, 49
	v_readlane_b32 s76, v252, 50
	v_readlane_b32 s77, v252, 51
	v_readlane_b32 s78, v252, 52
	v_readlane_b32 s79, v252, 53
	v_readlane_b32 s80, v252, 54
	v_readlane_b32 s81, v252, 55
.LBB0_1396:
	v_readfirstlane_b32 s101, v0
	v_readfirstlane_b32 s100, v156
	v_and_b32_e32 v253, 63, v0
	s_lshr_b32 s101, s101, 6
	v_lshlrev_b32_e32 v254, 6, v253
	s_mul_i32 s101, s101, 0x3000
	v_lshlrev_b32_e32 v253, 4, v253
	s_add_i32 s101, s101, 0xb400
	s_add_u32 s98, s82, s100
	s_addc_u32 s99, s83, 0
	v_add_u32_e32 v254, s101, v254
	s_add_u32 s98, s98, 0x7000000
	s_addc_u32 s99, s99, 0
	s_mov_b32 m0, s101
	s_nop 0
	global_load_lds_dwordx4 v253, s[98:99]
	global_load_lds_dwordx4 v253, s[98:99] offset:1024
	global_load_lds_dwordx4 v253, s[98:99] offset:2048
	global_load_lds_dwordx4 v253, s[98:99] offset:3072
	s_add_u32 s98, s98, 0x100000
	s_addc_u32 s99, s99, 0
	s_addk_i32 s101, 0x1000
	s_mov_b32 m0, s101
	s_nop 0
	global_load_lds_dwordx4 v253, s[98:99]
	global_load_lds_dwordx4 v253, s[98:99] offset:1024
	global_load_lds_dwordx4 v253, s[98:99] offset:2048
	global_load_lds_dwordx4 v253, s[98:99] offset:3072
	s_add_u32 s98, s98, 0x100000
	s_addc_u32 s99, s99, 0
	s_addk_i32 s101, 0x1000
	s_mov_b32 m0, s101
	s_nop 0
	global_load_lds_dwordx4 v253, s[98:99]
	global_load_lds_dwordx4 v253, s[98:99] offset:1024
	global_load_lds_dwordx4 v253, s[98:99] offset:2048
	global_load_lds_dwordx4 v253, s[98:99] offset:3072
	v_lshl_add_u64 v[98:99], s[82:83], 0, v[158:159]
	v_add_co_u32_e32 v86, vcc, 0x7400000, v98
	v_lshl_add_u64 v[100:101], s[82:83], 0, v[156:157]
	s_nop 0
	v_addc_co_u32_e32 v87, vcc, 0, v99, vcc
	s_mov_b64 s[64:65], 0x7000000
	v_add_co_u32_e32 v90, vcc, 0x7000000, v100
	v_lshl_add_u64 v[88:89], v[100:101], 0, s[64:65]
	s_nop 0
	v_addc_co_u32_e32 v91, vcc, 0, v101, vcc
	s_mov_b32 s3, 0x7410000
	global_load_dword v179, v[86:87], off
	v_add_co_u32_e32 v86, vcc, s3, v98
	s_mov_b32 s3, 0x7100000
	s_nop 0
	v_addc_co_u32_e32 v87, vcc, 0, v99, vcc
	global_load_dword v196, v[86:87], off
	v_add_co_u32_e32 v86, vcc, s3, v100
	s_mov_b32 s3, 0x7420000
	s_nop 0
	v_addc_co_u32_e32 v87, vcc, 0, v101, vcc
	v_add_co_u32_e32 v114, vcc, s3, v98
	s_mov_b32 s3, 0x7200000
	s_nop 0
	v_addc_co_u32_e32 v115, vcc, 0, v99, vcc
	v_add_co_u32_e32 v184, vcc, s3, v100
	s_mov_b64 s[64:65], 0x7100000
	s_nop 0
	v_addc_co_u32_e32 v185, vcc, 0, v101, vcc
	s_mov_b32 s3, 0x7430000
	v_lshl_add_u64 v[90:91], v[100:101], 0, s[64:65]
	s_mov_b64 s[64:65], 0x7200000
	v_add_co_u32_e32 v98, vcc, s3, v98
	v_lshl_add_u64 v[116:117], v[100:101], 0, s[64:65]
	s_nop 0
	v_addc_co_u32_e32 v99, vcc, 0, v99, vcc
	s_mov_b32 s3, 0x7300000
	s_nop 0
	s_nop 0
	global_load_dword v197, v[114:115], off
	s_nop 0
	s_nop 0
	global_load_dword v198, v[98:99], off
	s_mov_b64 s[64:65], 0x7300000
	v_add_co_u32_e32 v98, vcc, s3, v100
	v_lshl_add_u64 v[192:193], v[100:101], 0, s[64:65]
	s_nop 0
	v_addc_co_u32_e32 v99, vcc, 0, v101, vcc
	global_load_dwordx4 v[188:191], v[98:99], off
	s_nop 0
	global_load_dwordx4 v[98:101], v[192:193], off offset:48
	global_load_dwordx4 v[114:117], v[192:193], off offset:32
	s_nop 0
	global_load_dwordx4 v[192:195], v[192:193], off offset:16
	s_waitcnt vmcnt(8)
	ds_read_b128 v[82:85], v254 offset:48
	ds_read_b128 v[94:97], v254 offset:32
	ds_read_b128 v[110:113], v254 offset:16
	ds_read_b128 v[126:129], v254 offset:0
	ds_read_b128 v[180:183], v254 offset:4096
	ds_read_b128 v[86:89], v254 offset:4144
	ds_read_b128 v[102:105], v254 offset:4128
	ds_read_b128 v[118:121], v254 offset:4112
	ds_read_b128 v[90:93], v254 offset:8240
	ds_read_b128 v[106:109], v254 offset:8224
	ds_read_b128 v[122:125], v254 offset:8208
	ds_read_b128 v[184:187], v254 offset:8192
	s_waitcnt vmcnt(0) lgkmcnt(0)
	v_add_f32_e32 v179, v179, v196
	s_waitcnt vmcnt(0)
	v_add_f32_e32 v196, v197, v198
	v_add_f32_e32 v179, v179, v196
	v_fmamk_f32 v179, v179, 0x3a800000, v166
	s_mov_b32 s3, 0xf800000
	v_cmp_gt_f32_e32 vcc, s3, v179
	v_mul_f32_e32 v196, 0x4f800000, v179
	v_add_f32_e32 v126, v126, v180
	v_cndmask_b32_e32 v179, v179, v196, vcc
	v_sqrt_f32_e32 v196, v179
	s_waitcnt vmcnt(0)
	v_add_f32_e32 v180, v184, v188
	v_add_f32_e32 v126, v126, v180
	v_add_f32_e32 v127, v127, v181
	v_add_u32_e32 v197, -1, v196
	v_fma_f32 v198, -v197, v196, v179
	v_cmp_ge_f32_e64 s[64:65], 0, v198
	v_add_u32_e32 v198, 1, v196
	v_add_f32_e32 v180, v185, v189
	v_cndmask_b32_e64 v197, v196, v197, s[64:65]
	v_fma_f32 v196, -v198, v196, v179
	v_cmp_lt_f32_e64 s[64:65], 0, v196
	v_add_f32_e32 v82, v82, v86
	s_waitcnt vmcnt(0)
	v_add_f32_e32 v86, v90, v98
	v_cndmask_b32_e64 v196, v197, v198, s[64:65]
	v_mul_f32_e32 v197, 0x37800000, v196
	v_cndmask_b32_e32 v196, v196, v197, vcc
	v_cmp_class_f32_e32 vcc, v179, v168
	v_add_f32_e32 v127, v127, v180
	v_add_f32_e32 v128, v128, v182
	v_cndmask_b32_e32 v179, v196, v179, vcc
	v_div_scale_f32 v196, s[64:65], v179, v179, 1.0
	v_rcp_f32_e32 v197, v196
	v_add_f32_e32 v180, v186, v190
	v_add_f32_e32 v110, v110, v118
	s_waitcnt vmcnt(0)
	v_add_f32_e32 v118, v122, v192
	v_fma_f32 v198, -v196, v197, 1.0
	v_fmac_f32_e32 v197, v198, v197
	v_div_scale_f32 v198, vcc, 1.0, v179, 1.0
	v_mul_f32_e32 v199, v198, v197
	v_fma_f32 v200, -v196, v199, v198
	v_fmac_f32_e32 v199, v200, v197
	v_fma_f32 v196, -v196, v199, v198
	v_div_fmas_f32 v196, v196, v197, v199
	v_add_f32_e32 v82, v82, v86
	v_add_f32_e32 v83, v83, v87
	v_add_f32_e32 v86, v91, v99
	v_div_fixup_f32 v179, v196, v179, 1.0
	v_add_f32_e32 v128, v128, v180
	v_add_f32_e32 v129, v129, v183
	v_add_f32_e32 v180, v187, v191
	v_add_f32_e32 v110, v110, v118
	v_add_f32_e32 v111, v111, v119
	v_add_f32_e32 v118, v123, v193
	v_add_f32_e32 v83, v83, v86
	v_add_f32_e32 v84, v84, v88
	v_add_f32_e32 v86, v92, v100
	v_fma_f32 v126, v126, v179, v66
	v_fma_f32 v127, v127, v179, v67
	v_add_f32_e32 v129, v129, v180
	v_add_f32_e32 v111, v111, v118
	v_add_f32_e32 v112, v112, v120
	v_add_f32_e32 v118, v124, v194
	v_add_f32_e32 v94, v94, v102
	v_add_f32_e32 v102, v106, v114
	v_add_f32_e32 v84, v84, v86
	v_add_f32_e32 v85, v85, v89
	v_add_f32_e32 v86, v93, v101
	v_fma_f32 v128, v128, v179, v68
	v_fma_f32 v129, v129, v179, v69
	v_add_f32_e32 v112, v112, v118
	v_add_f32_e32 v113, v113, v121
	v_add_f32_e32 v118, v125, v195
	v_add_f32_e32 v94, v94, v102
	v_add_f32_e32 v95, v95, v103
	v_add_f32_e32 v102, v107, v115
	v_add_f32_e32 v85, v85, v86
	v_max_f32_e32 v86, v126, v127
	v_fma_f32 v110, v110, v179, v70
	v_fma_f32 v111, v111, v179, v71
	v_add_f32_e32 v113, v113, v118
	v_add_f32_e32 v95, v95, v102
	v_add_f32_e32 v96, v96, v104
	v_add_f32_e32 v102, v108, v116
	v_max3_f32 v86, v86, v128, v129
	v_fma_f32 v112, v112, v179, v72
	v_fma_f32 v113, v113, v179, v73
	v_add_f32_e32 v96, v96, v102
	v_add_f32_e32 v97, v97, v105
	v_add_f32_e32 v102, v109, v117
	v_max3_f32 v86, v86, v110, v111
	v_fma_f32 v94, v179, v94, v74
	v_fma_f32 v95, v179, v95, v75
	v_add_f32_e32 v97, v97, v102
	v_max3_f32 v86, v86, v112, v113
	v_fma_f32 v96, v179, v96, v76
	v_fma_f32 v97, v179, v97, v77
	v_max3_f32 v86, v86, v94, v95
	v_fma_f32 v82, v179, v82, v78
	v_fma_f32 v83, v179, v83, v79
	v_max3_f32 v86, v86, v96, v97
	v_fma_f32 v84, v179, v84, v80
	v_fma_f32 v85, v179, v85, v81
	v_max3_f32 v86, v86, v82, v83
	v_max3_f32 v86, v86, v84, v85
	v_sub_f32_e32 v87, v126, v86
	v_mul_f32_e32 v88, 0x3fb8aa3b, v87
	v_fma_f32 v89, v87, s1, -v88
	v_rndne_f32_e32 v90, v88
	v_fmac_f32_e32 v89, 0x32a5705f, v87
	v_sub_f32_e32 v88, v88, v90
	v_add_f32_e32 v88, v88, v89
	v_exp_f32_e32 v88, v88
	v_cvt_i32_f32_e32 v89, v90
	v_cmp_ngt_f32_e32 vcc, s6, v87
	v_sub_f32_e32 v82, v82, v86
	v_sub_f32_e32 v83, v83, v86
	v_ldexp_f32 v88, v88, v89
	v_sub_f32_e32 v89, v127, v86
	v_mul_f32_e32 v90, 0x3fb8aa3b, v89
	v_fma_f32 v91, v89, s1, -v90
	v_rndne_f32_e32 v92, v90
	v_fmac_f32_e32 v91, 0x32a5705f, v89
	v_sub_f32_e32 v90, v90, v92
	v_add_f32_e32 v90, v90, v91
	v_exp_f32_e32 v90, v90
	v_cvt_i32_f32_e32 v91, v92
	v_cndmask_b32_e32 v88, 0, v88, vcc
	v_cmp_nlt_f32_e32 vcc, s7, v87
	s_movk_i32 s3, 0x5ff
	v_ldexp_f32 v90, v90, v91
	v_cndmask_b32_e32 v87, v173, v88, vcc
	v_cmp_ngt_f32_e32 vcc, s6, v89
	v_cndmask_b32_e64 v88, 0, v87, s[30:31]
	v_lshl_add_u64 v[158:159], v[158:159], 0, s[96:97]
	v_cndmask_b32_e32 v90, 0, v90, vcc
	v_cmp_nlt_f32_e32 vcc, s7, v89
	v_lshl_add_u64 v[156:157], v[156:157], 0, s[14:15]
	s_nop 0
	v_cndmask_b32_e32 v89, v173, v90, vcc
	v_add_f32_e32 v87, v87, v89
	v_cndmask_b32_e64 v88, v88, v89, s[34:35]
	v_sub_f32_e32 v89, v128, v86
	v_mul_f32_e32 v90, 0x3fb8aa3b, v89
	v_fma_f32 v91, v89, s1, -v90
	v_rndne_f32_e32 v92, v90
	v_fmac_f32_e32 v91, 0x32a5705f, v89
	v_sub_f32_e32 v90, v90, v92
	v_add_f32_e32 v90, v90, v91
	v_exp_f32_e32 v90, v90
	v_cvt_i32_f32_e32 v91, v92
	v_cmp_ngt_f32_e32 vcc, s6, v89
	v_ldexp_f32 v90, v90, v91
	s_nop 0
	v_cndmask_b32_e32 v90, 0, v90, vcc
	v_cmp_nlt_f32_e32 vcc, s7, v89
	s_nop 1
	v_cndmask_b32_e32 v89, v173, v90, vcc
	v_add_f32_e32 v87, v89, v87
	v_cndmask_b32_e64 v88, v88, v89, s[36:37]
	v_sub_f32_e32 v89, v129, v86
	v_mul_f32_e32 v90, 0x3fb8aa3b, v89
	v_fma_f32 v91, v89, s1, -v90
	v_rndne_f32_e32 v92, v90
	v_fmac_f32_e32 v91, 0x32a5705f, v89
	v_sub_f32_e32 v90, v90, v92
	v_add_f32_e32 v90, v90, v91
	v_exp_f32_e32 v90, v90
	v_cvt_i32_f32_e32 v91, v92
	v_cmp_ngt_f32_e32 vcc, s6, v89
	v_ldexp_f32 v90, v90, v91
	s_nop 0
	v_cndmask_b32_e32 v90, 0, v90, vcc
	v_cmp_nlt_f32_e32 vcc, s7, v89
	s_nop 1
	v_cndmask_b32_e32 v89, v173, v90, vcc
	v_add_f32_e32 v87, v89, v87
	v_cndmask_b32_e64 v88, v88, v89, s[38:39]
	v_sub_f32_e32 v89, v110, v86
	v_mul_f32_e32 v90, 0x3fb8aa3b, v89
	v_fma_f32 v91, v89, s1, -v90
	v_rndne_f32_e32 v92, v90
	v_fmac_f32_e32 v91, 0x32a5705f, v89
	v_sub_f32_e32 v90, v90, v92
	v_add_f32_e32 v90, v90, v91
	v_exp_f32_e32 v90, v90
	v_cvt_i32_f32_e32 v91, v92
	v_cmp_ngt_f32_e32 vcc, s6, v89
	v_ldexp_f32 v90, v90, v91
	s_nop 0
	v_cndmask_b32_e32 v90, 0, v90, vcc
	v_cmp_nlt_f32_e32 vcc, s7, v89
	s_nop 1
	v_cndmask_b32_e32 v89, v173, v90, vcc
	v_add_f32_e32 v87, v89, v87
	v_cndmask_b32_e64 v88, v88, v89, s[40:41]
	v_sub_f32_e32 v89, v111, v86
	v_mul_f32_e32 v90, 0x3fb8aa3b, v89
	v_fma_f32 v91, v89, s1, -v90
	v_rndne_f32_e32 v92, v90
	v_fmac_f32_e32 v91, 0x32a5705f, v89
	v_sub_f32_e32 v90, v90, v92
	v_add_f32_e32 v90, v90, v91
	v_exp_f32_e32 v90, v90
	v_cvt_i32_f32_e32 v91, v92
	v_cmp_ngt_f32_e32 vcc, s6, v89
	v_ldexp_f32 v90, v90, v91
	s_nop 0
	v_cndmask_b32_e32 v90, 0, v90, vcc
	v_cmp_nlt_f32_e32 vcc, s7, v89
	s_nop 1
	v_cndmask_b32_e32 v89, v173, v90, vcc
	v_add_f32_e32 v87, v89, v87
	v_cndmask_b32_e64 v88, v88, v89, s[42:43]
	v_sub_f32_e32 v89, v112, v86
	v_mul_f32_e32 v90, 0x3fb8aa3b, v89
	v_fma_f32 v91, v89, s1, -v90
	v_rndne_f32_e32 v92, v90
	v_fmac_f32_e32 v91, 0x32a5705f, v89
	v_sub_f32_e32 v90, v90, v92
	v_add_f32_e32 v90, v90, v91
	v_exp_f32_e32 v90, v90
	v_cvt_i32_f32_e32 v91, v92
	v_cmp_ngt_f32_e32 vcc, s6, v89
	v_ldexp_f32 v90, v90, v91
	s_nop 0
	v_cndmask_b32_e32 v90, 0, v90, vcc
	v_cmp_nlt_f32_e32 vcc, s7, v89
	s_nop 1
	v_cndmask_b32_e32 v89, v173, v90, vcc
	v_add_f32_e32 v87, v89, v87
	v_cndmask_b32_e64 v88, v88, v89, s[44:45]
	v_sub_f32_e32 v89, v113, v86
	v_mul_f32_e32 v90, 0x3fb8aa3b, v89
	v_fma_f32 v91, v89, s1, -v90
	v_rndne_f32_e32 v92, v90
	v_fmac_f32_e32 v91, 0x32a5705f, v89
	v_sub_f32_e32 v90, v90, v92
	v_add_f32_e32 v90, v90, v91
	v_exp_f32_e32 v90, v90
	v_cvt_i32_f32_e32 v91, v92
	v_cmp_ngt_f32_e32 vcc, s6, v89
	v_ldexp_f32 v90, v90, v91
	s_nop 0
	v_cndmask_b32_e32 v90, 0, v90, vcc
	v_cmp_nlt_f32_e32 vcc, s7, v89
	s_nop 1
	v_cndmask_b32_e32 v89, v173, v90, vcc
	v_add_f32_e32 v87, v89, v87
	v_cndmask_b32_e64 v88, v88, v89, s[46:47]
	v_sub_f32_e32 v89, v94, v86
	v_mul_f32_e32 v90, 0x3fb8aa3b, v89
	v_fma_f32 v91, v89, s1, -v90
	v_rndne_f32_e32 v92, v90
	v_fmac_f32_e32 v91, 0x32a5705f, v89
	v_sub_f32_e32 v90, v90, v92
	v_add_f32_e32 v90, v90, v91
	v_exp_f32_e32 v90, v90
	v_cvt_i32_f32_e32 v91, v92
	v_cmp_ngt_f32_e32 vcc, s6, v89
	v_ldexp_f32 v90, v90, v91
	s_nop 0
	v_cndmask_b32_e32 v90, 0, v90, vcc
	v_cmp_nlt_f32_e32 vcc, s7, v89
	s_nop 1
	v_cndmask_b32_e32 v89, v173, v90, vcc
	v_add_f32_e32 v87, v89, v87
	v_cndmask_b32_e64 v88, v88, v89, s[48:49]
	v_sub_f32_e32 v89, v95, v86
	v_mul_f32_e32 v90, 0x3fb8aa3b, v89
	v_fma_f32 v91, v89, s1, -v90
	v_rndne_f32_e32 v92, v90
	v_fmac_f32_e32 v91, 0x32a5705f, v89
	v_sub_f32_e32 v90, v90, v92
	v_add_f32_e32 v90, v90, v91
	v_exp_f32_e32 v90, v90
	v_cvt_i32_f32_e32 v91, v92
	v_cmp_ngt_f32_e32 vcc, s6, v89
	v_ldexp_f32 v90, v90, v91
	s_nop 0
	v_cndmask_b32_e32 v90, 0, v90, vcc
	v_cmp_nlt_f32_e32 vcc, s7, v89
	s_nop 1
	v_cndmask_b32_e32 v89, v173, v90, vcc
	v_add_f32_e32 v87, v89, v87
	v_cndmask_b32_e64 v88, v88, v89, s[50:51]
	v_sub_f32_e32 v89, v96, v86
	v_mul_f32_e32 v90, 0x3fb8aa3b, v89
	v_fma_f32 v91, v89, s1, -v90
	v_rndne_f32_e32 v92, v90
	v_fmac_f32_e32 v91, 0x32a5705f, v89
	v_sub_f32_e32 v90, v90, v92
	v_add_f32_e32 v90, v90, v91
	v_exp_f32_e32 v90, v90
	v_cvt_i32_f32_e32 v91, v92
	v_cmp_ngt_f32_e32 vcc, s6, v89
	v_ldexp_f32 v90, v90, v91
	s_nop 0
	v_cndmask_b32_e32 v90, 0, v90, vcc
	v_cmp_nlt_f32_e32 vcc, s7, v89
	s_nop 1
	v_cndmask_b32_e32 v89, v173, v90, vcc
	v_add_f32_e32 v87, v89, v87
	v_cndmask_b32_e64 v88, v88, v89, s[52:53]
	v_sub_f32_e32 v89, v97, v86
	v_mul_f32_e32 v90, 0x3fb8aa3b, v89
	v_fma_f32 v91, v89, s1, -v90
	v_rndne_f32_e32 v92, v90
	v_fmac_f32_e32 v91, 0x32a5705f, v89
	v_sub_f32_e32 v90, v90, v92
	v_add_f32_e32 v90, v90, v91
	v_exp_f32_e32 v90, v90
	v_cvt_i32_f32_e32 v91, v92
	v_cmp_ngt_f32_e32 vcc, s6, v89
	v_ldexp_f32 v90, v90, v91
	s_nop 0
	v_cndmask_b32_e32 v90, 0, v90, vcc
	v_cmp_nlt_f32_e32 vcc, s7, v89
	s_nop 1
	v_cndmask_b32_e32 v89, v173, v90, vcc
	v_add_f32_e32 v87, v89, v87
	v_cndmask_b32_e64 v88, v88, v89, s[54:55]
	v_mul_f32_e32 v89, 0x3fb8aa3b, v82
	v_fma_f32 v90, v82, s1, -v89
	v_rndne_f32_e32 v91, v89
	v_fmac_f32_e32 v90, 0x32a5705f, v82
	v_sub_f32_e32 v89, v89, v91
	v_add_f32_e32 v89, v89, v90
	v_exp_f32_e32 v89, v89
	v_cvt_i32_f32_e32 v90, v91
	v_cmp_ngt_f32_e32 vcc, s6, v82
	v_ldexp_f32 v89, v89, v90
	s_nop 0
	v_cndmask_b32_e32 v89, 0, v89, vcc
	v_cmp_nlt_f32_e32 vcc, s7, v82
	s_nop 1
	v_cndmask_b32_e32 v82, v173, v89, vcc
	v_add_f32_e32 v87, v82, v87
	v_cndmask_b32_e64 v82, v88, v82, s[56:57]
	v_mul_f32_e32 v88, 0x3fb8aa3b, v83
	v_fma_f32 v89, v83, s1, -v88
	v_rndne_f32_e32 v90, v88
	v_fmac_f32_e32 v89, 0x32a5705f, v83
	v_sub_f32_e32 v88, v88, v90
	v_add_f32_e32 v88, v88, v89
	v_exp_f32_e32 v88, v88
	v_cvt_i32_f32_e32 v89, v90
	v_cmp_ngt_f32_e32 vcc, s6, v83
	v_ldexp_f32 v88, v88, v89
	s_nop 0
	v_cndmask_b32_e32 v88, 0, v88, vcc
	v_cmp_nlt_f32_e32 vcc, s7, v83
	s_nop 1
	v_cndmask_b32_e32 v83, v173, v88, vcc
	v_add_f32_e32 v87, v83, v87
	v_cndmask_b32_e64 v82, v82, v83, s[58:59]
	v_sub_f32_e32 v83, v84, v86
	v_mul_f32_e32 v84, 0x3fb8aa3b, v83
	v_fma_f32 v88, v83, s1, -v84
	v_rndne_f32_e32 v89, v84
	v_fmac_f32_e32 v88, 0x32a5705f, v83
	v_sub_f32_e32 v84, v84, v89
	v_add_f32_e32 v84, v84, v88
	v_exp_f32_e32 v84, v84
	v_cvt_i32_f32_e32 v88, v89
	v_cmp_ngt_f32_e32 vcc, s6, v83
	v_ldexp_f32 v84, v84, v88
	s_nop 0
	v_cndmask_b32_e32 v84, 0, v84, vcc
	v_cmp_nlt_f32_e32 vcc, s7, v83
	s_nop 1
	v_cndmask_b32_e32 v83, v173, v84, vcc
	v_add_f32_e32 v84, v83, v87
	v_cndmask_b32_e64 v82, v82, v83, s[60:61]
	v_sub_f32_e32 v83, v85, v86
	v_mul_f32_e32 v85, 0x3fb8aa3b, v83
	v_fma_f32 v86, v83, s1, -v85
	v_rndne_f32_e32 v87, v85
	v_fmac_f32_e32 v86, 0x32a5705f, v83
	v_sub_f32_e32 v85, v85, v87
	v_add_f32_e32 v85, v85, v86
	v_exp_f32_e32 v85, v85
	v_cvt_i32_f32_e32 v86, v87
	v_cmp_ngt_f32_e32 vcc, s6, v83
	v_ldexp_f32 v85, v85, v86
	s_nop 0
	v_cndmask_b32_e32 v85, 0, v85, vcc
	v_cmp_nlt_f32_e32 vcc, s7, v83
	s_nop 1
	v_cndmask_b32_e32 v83, v173, v85, vcc
	v_add_f32_e32 v84, v83, v84
	v_cndmask_b32_e64 v82, v82, v83, s[62:63]
	v_div_scale_f32 v83, s[64:65], v84, v84, v82
	v_rcp_f32_e32 v85, v83
	s_nop 0
	v_fma_f32 v86, -v83, v85, 1.0
	v_fmac_f32_e32 v85, v86, v85
	v_div_scale_f32 v86, vcc, v82, v84, v82
	v_mul_f32_e32 v87, v86, v85
	v_fma_f32 v88, -v83, v87, v86
	v_fmac_f32_e32 v87, v88, v85
	v_fma_f32 v83, -v83, v87, v86
	v_div_fmas_f32 v83, v83, v85, v87
	v_div_fixup_f32 v82, v83, v84, v82
	v_lshl_add_u64 v[84:85], v[154:155], 0, s[86:87]
	v_subrev_co_u32_e32 v84, vcc, 0, v84
	s_add_u32 s86, s86, 0x200
	s_nop 0
	v_subb_co_u32_e32 v85, vcc, v85, v82, vcc
	v_add_u32_e32 v82, s86, v0
	v_add_u32_e32 v82, 0xfffffe01, v82
	s_addc_u32 s87, s87, 0
	v_cmp_lt_u32_e32 vcc, s3, v82
	ds_write_b64 v177, v[84:85]
	ds_write2st64_b32 v134, v167, v179 offset1:32
	v_add_u32_e32 v134, 0x800, v134
	v_add_u32_e32 v177, 0x1000, v177
	s_or_b64 s[66:67], vcc, s[66:67]
	s_andn2_b64 exec, exec, s[66:67]
	s_cbranch_execnz .LBB0_1396
	s_or_b64 exec, exec, s[66:67]
	s_and_b64 vcc, exec, s[28:29]
	s_waitcnt lgkmcnt(0)
	s_barrier
	s_cbranch_vccz .LBB0_1407
	v_readlane_b32 s36, v252, 42
	s_cmpk_gt_u32 s85, 0xcc7f
	v_readlane_b32 s37, v252, 43
	v_readlane_b32 s38, v252, 44
	v_readlane_b32 s39, v252, 45
	v_readlane_b32 s42, v252, 48
	v_readlane_b32 s43, v252, 49
	v_readlane_b32 s44, v252, 50
	v_readlane_b32 s45, v252, 51
	v_readlane_b32 s46, v252, 52
	v_readlane_b32 s47, v252, 53
	v_readlane_b32 s40, v252, 46
	v_readlane_b32 s41, v252, 47
	v_readlane_b32 s48, v252, 54
	v_readlane_b32 s49, v252, 55
	v_readlane_b32 s50, v252, 56
	v_readlane_b32 s51, v252, 57
	s_cbranch_scc1 .LBB0_1424
	s_cmpk_gt_u32 s85, 0x87f
	s_mov_b64 s[30:31], -1
	v_writelane_b32 v252, s34, 58
	s_nop 1
	v_writelane_b32 v252, s35, 59
	s_cbranch_scc0 .LBB0_1420
	s_cmpk_gt_u32 s85, 0x97f
	s_cbranch_scc0 .LBB0_1408
	s_cmpk_gt_u32 s85, 0xa7f
	s_cbranch_scc0 .LBB0_1409
	s_cmpk_gt_u32 s85, 0xc7f
	s_cbranch_scc0 .LBB0_1410
	s_add_i32 s2, s85, 0xfffff380
	s_mul_i32 s3, s2, 0xaaab
	s_lshr_b32 s5, s3, 27
	s_mul_i32 s13, s5, 0xfffff400
	s_add_i32 s13, s13, s2
	s_cmpk_gt_i32 s13, 0x7ff
	s_mov_b64 s[2:3], -1
	s_cbranch_scc0 .LBB0_1405
	s_lshl_b32 s2, s5, 23
	s_add_u32 s2, s46, s2
	s_addc_u32 s3, s47, 0
	v_writelane_b32 v251, s2, 57
	s_nop 1
	v_writelane_b32 v251, s3, 58
	s_lshl_b32 s2, s13, 1
	s_and_b32 s2, s2, 0x7fffffc0
	s_add_i32 s26, s2, 0xfffff000
	s_lshl_b32 s2, s85, 5
	s_and_b32 s30, s2, 0x3e0
	s_lshl_b32 s2, s5, 10
	s_or_b32 s2, s2, s30
	v_writelane_b32 v251, s2, 56
	s_mov_b64 s[2:3], 0
